# P0 filter-MLP weight staging: the w1 loads are issued together and overlap the w2/w3 loads (were five dependent load/wait/LDS-write rounds)
# speedup vs baseline: 1.0021x; 1.0021x over previous
.LBB0_22:
	s_cmp_lg_u32 s38, s7
	s_mov_b64 s[38:39], -1
	s_cbranch_scc0 .LBB0_55
	s_mov_b64 s[100:101], 0
	v_readlane_b32 s0, v254, 22
	v_readlane_b32 s1, v254, 23
	s_barrier
	s_and_saveexec_b64 s[38:39], s[0:1]
	s_cbranch_execz .LBB0_38
	v_readlane_b32 s0, v254, 30
	s_mov_b64 s[44:45], -1
	v_mov_b32_e32 v0, v8
	v_mov_b32_e32 v1, v27
	v_readlane_b32 s1, v254, 31
	s_and_saveexec_b64 s[42:43], s[0:1]
	s_cbranch_execz .LBB0_35
	v_readlane_b32 s0, v254, 34
	v_mov_b32_e32 v4, 0
	v_mov_b64_e32 v[0:1], v[8:9]
	v_readlane_b32 s1, v254, 35
	s_and_saveexec_b64 s[44:45], s[0:1]
	s_cbranch_execz .LBB0_29
	s_mov_b32 s58, 0
	s_mov_b64 s[54:55], 0
	v_mov_b32_e32 v2, v76
	v_mov_b32_e32 v3, v65
	v_mov_b64_e32 v[0:1], v[8:9]

.LBB0_35:
	s_or_b64 exec, exec, s[42:43]
	s_and_b64 exec, exec, s[44:45]
	s_cbranch_execz .LBB0_38
	s_add_i32 s42, 0, 0x2000
	v_add_u32_e32 v186, s42, v1
	v_ashrrev_i32_e32 v1, 31, v0
	v_add_u32_e32 v185, 0xfffffe00, v0
	v_lshl_add_u64 v[0:1], v[0:1], 2, s[50:51]
	s_mov_b64 s[100:101], exec
	s_mov_b32 s98, 0x1000
	s_mov_b32 s99, 0
	global_load_dword v180, v[0:1], off
	v_cmp_gt_i32_e32 vcc, 0x440, v185
	s_and_b64 exec, s[100:101], vcc
	global_load_dword v181, v[0:1], off offset:2048
	v_cmp_gt_i32_e32 vcc, 0x240, v185
	s_and_b64 exec, s[100:101], vcc
	v_lshl_add_u64 v[188:189], v[0:1], 0, s[98:99]
	global_load_dword v182, v[188:189], off
	v_cmp_gt_i32_e32 vcc, 64, v185
	s_and_b64 exec, s[100:101], vcc
	global_load_dword v183, v[188:189], off offset:2048
	v_cmp_gt_i32_e32 vcc, 0xfffffe40, v185
	s_and_b64 exec, s[100:101], vcc
	v_lshl_add_u64 v[188:189], v[188:189], 0, s[98:99]
	global_load_dword v184, v[188:189], off

.LBB0_53:
	s_or_b64 exec, exec, s[38:39]
	s_mov_b64 s[98:99], exec
	s_waitcnt vmcnt(0)
	s_mov_b64 exec, s[100:101]
	ds_write_b32 v186, v180
	v_cmp_gt_i32_e32 vcc, 0x440, v185
	s_and_b64 exec, s[100:101], vcc
	ds_write_b32 v186, v181 offset:2048
	v_cmp_gt_i32_e32 vcc, 0x240, v185
	s_and_b64 exec, s[100:101], vcc
	ds_write_b32 v186, v182 offset:4096
	v_cmp_gt_i32_e32 vcc, 64, v185
	s_and_b64 exec, s[100:101], vcc
	ds_write_b32 v186, v183 offset:6144
	v_cmp_gt_i32_e32 vcc, 0xfffffe40, v185
	s_and_b64 exec, s[100:101], vcc
	ds_write_b32 v186, v184 offset:8192
	s_mov_b64 exec, s[98:99]
	v_readlane_b32 s0, v253, 57
	v_readlane_b32 s1, v253, 58
	s_andn2_b64 vcc, exec, s[0:1]
	v_mov_b32_e32 v44, v78
	v_readlane_b32 s58, v253, 0
	s_waitcnt lgkmcnt(0)
	s_barrier
	s_cbranch_vccz .LBB0_59
